# row-max permlane exchange and zero-add fold extended to the ctx-A and ctx-B attention instantiations
# speedup vs baseline: 1.0037x; 1.0037x over previous
.LBB0_271:
	v_sub_f32_e32 v4, v96, v1
	v_exp_f32_e32 v9, v4
	v_sub_f32_e32 v5, v97, v1
	v_exp_f32_e32 v10, v5
	v_sub_f32_e32 v5, v98, v1
	v_exp_f32_e32 v11, v5
	v_sub_f32_e32 v5, v99, v1
	v_exp_f32_e32 v13, v5
	v_sub_f32_e32 v5, v100, v1
	v_exp_f32_e32 v14, v5
	v_sub_f32_e32 v5, v101, v1
	v_add_f32_e32 v4, v10, v9
	v_exp_f32_e32 v15, v5
	v_sub_f32_e32 v5, v102, v1
	v_add_f32_e32 v4, v11, v4
	v_exp_f32_e32 v96, v5
	v_sub_f32_e32 v5, v103, v1
	v_add_f32_e32 v4, v13, v4
	v_exp_f32_e32 v97, v5
	v_sub_f32_e32 v5, v104, v1
	v_add_f32_e32 v4, v14, v4
	v_exp_f32_e32 v5, v5
	v_sub_f32_e32 v6, v105, v1
	v_add_f32_e32 v4, v15, v4
	v_exp_f32_e32 v6, v6
	v_sub_f32_e32 v7, v106, v1
	v_add_f32_e32 v4, v96, v4
	v_exp_f32_e32 v7, v7
	v_sub_f32_e32 v12, v107, v1
	v_add_f32_e32 v4, v97, v4
	v_exp_f32_e32 v12, v12
	v_sub_f32_e32 v98, v108, v1
	v_add_f32_e32 v4, v5, v4
	v_exp_f32_e32 v98, v98
	v_sub_f32_e32 v99, v109, v1
	v_add_f32_e32 v4, v6, v4
	v_exp_f32_e32 v99, v99
	v_sub_f32_e32 v100, v110, v1
	v_add_f32_e32 v4, v7, v4
	v_exp_f32_e32 v100, v100
	v_sub_f32_e32 v101, v111, v1
	v_add_f32_e32 v4, v12, v4
	v_exp_f32_e32 v101, v101
	v_add_f32_e32 v4, v98, v4
	v_add_f32_e32 v4, v99, v4
	v_add_f32_e32 v4, v100, v4
	v_add_f32_e32 v4, v101, v4
	v_add_f32_e32 v3, v3, v4
	v_cvt_pk_bf16_f32 v4, v5, v6
	v_cvt_pk_bf16_f32 v5, v7, v12
	v_cvt_pk_bf16_f32 v12, v9, v10
	v_sub_f32_e32 v9, v80, v205
	v_cvt_pk_bf16_f32 v13, v11, v13
	v_exp_f32_e32 v9, v9
	v_sub_f32_e32 v11, v81, v205
	v_exp_f32_e32 v11, v11
	v_sub_f32_e32 v80, v82, v205
	v_exp_f32_e32 v81, v80
	v_sub_f32_e32 v80, v83, v205
	v_exp_f32_e32 v82, v80
	v_sub_f32_e32 v80, v84, v205
	v_exp_f32_e32 v83, v80
	v_sub_f32_e32 v80, v85, v205
	v_add_f32_e32 v10, v11, v9
	v_exp_f32_e32 v84, v80
	v_sub_f32_e32 v80, v86, v205
	v_add_f32_e32 v10, v81, v10
	v_exp_f32_e32 v85, v80
	v_sub_f32_e32 v80, v87, v205
	v_add_f32_e32 v10, v82, v10
	v_exp_f32_e32 v86, v80
	v_sub_f32_e32 v80, v88, v205
	v_add_f32_e32 v10, v83, v10
	v_exp_f32_e32 v87, v80
	v_sub_f32_e32 v80, v89, v205
	v_add_f32_e32 v10, v84, v10
	v_exp_f32_e32 v88, v80
	v_sub_f32_e32 v80, v90, v205
	v_add_f32_e32 v10, v85, v10
	v_exp_f32_e32 v89, v80
	v_sub_f32_e32 v80, v91, v205
	v_add_f32_e32 v10, v86, v10
	v_exp_f32_e32 v90, v80
	v_sub_f32_e32 v80, v92, v205
	v_add_f32_e32 v10, v87, v10
	v_exp_f32_e32 v91, v80
	v_sub_f32_e32 v80, v93, v205
	v_add_f32_e32 v10, v88, v10
	v_exp_f32_e32 v92, v80
	v_sub_f32_e32 v80, v94, v205
	v_add_f32_e32 v10, v89, v10
	v_exp_f32_e32 v93, v80
	v_sub_f32_e32 v80, v95, v205
	v_add_f32_e32 v10, v90, v10
	v_exp_f32_e32 v94, v80
	v_add_f32_e32 v10, v91, v10
	v_add_f32_e32 v10, v92, v10
	v_add_f32_e32 v10, v93, v10
	v_add_f32_e32 v10, v94, v10
	v_add_f32_e32 v208, v8, v10
	v_cvt_pk_bf16_f32 v81, v81, v82
	v_cvt_pk_bf16_f32 v82, v83, v84
	v_cvt_pk_bf16_f32 v8, v87, v88
	v_lshl_add_u32 v84, v204, 1, v219
	v_lshl_add_u32 v88, v203, 1, v219
	v_cvt_pk_bf16_f32 v80, v9, v11
	v_cvt_pk_bf16_f32 v83, v85, v86
	v_cvt_pk_bf16_f32 v9, v89, v90
	v_cvt_pk_bf16_f32 v10, v91, v92
	ds_read_b64 v[238:239], v84 offset:8192
	ds_read_b64 v[242:243], v84 offset:12288
	ds_read_b64 v[240:241], v88 offset:8192
	ds_read_b64 v[244:245], v88 offset:12288
	v_cvt_pk_bf16_f32 v11, v93, v94
	v_cvt_pk_bf16_f32 v14, v14, v15
	v_cvt_pk_bf16_f32 v15, v96, v97
	s_waitcnt lgkmcnt(0)
	v_mfma_f32_32x32x16_bf16 v[64:79], v[238:241], v[12:15], v[64:79]
	v_cvt_pk_bf16_f32 v6, v98, v99
	v_cvt_pk_bf16_f32 v7, v100, v101
	s_add_i32 s39, s39, 1
	s_add_i32 s2, s40, 1
	s_cmp_lg_u32 s40, 2
	s_cselect_b32 s40, s2, 0
	s_mov_b64 s[2:3], 0x1000
	v_mfma_f32_32x32x16_bf16 v[32:47], v[238:241], v[80:83], v[32:47]
	v_lshl_add_u64 v[162:163], v[162:163], 0, s[22:23]
	v_lshl_add_u64 v[164:165], v[164:165], 0, s[2:3]
	v_lshl_add_u64 v[166:167], v[166:167], 0, s[24:25]
	s_cmp_lg_u32 s39, 39
	v_mfma_f32_32x32x16_bf16 v[48:63], v[242:245], v[12:15], v[48:63]
	v_lshl_add_u32 v12, v202, 1, v219
	ds_read2st64_b64 v[12:15], v12 offset0:16 offset1:24
	s_waitcnt lgkmcnt(0)
	v_mov_b32_e32 v84, v12
	v_mfma_f32_32x32x16_bf16 v[16:31], v[242:245], v[80:83], v[16:31]
	v_lshl_add_u32 v80, v201, 1, v219
	ds_read2st64_b64 v[80:83], v80 offset0:16 offset1:24
	v_mov_b32_e32 v85, v13
	s_waitcnt lgkmcnt(0)
	v_mov_b32_e32 v86, v80
	v_mov_b32_e32 v87, v81
	v_mov_b32_e32 v80, v14
	v_mov_b32_e32 v81, v15
	v_mfma_f32_32x32x16_bf16 v[64:79], v[84:87], v[4:7], v[64:79]
	v_mfma_f32_32x32x16_bf16 v[32:47], v[84:87], v[8:11], v[32:47]
	v_mfma_f32_32x32x16_bf16 v[48:63], v[80:83], v[4:7], v[48:63]
	v_mfma_f32_32x32x16_bf16 v[16:31], v[80:83], v[8:11], v[16:31]
	s_cbranch_scc0 .LBB0_282

.LBB0_290:
	v_sub_f32_e32 v4, v96, v1
	v_exp_f32_e32 v9, v4
	v_sub_f32_e32 v5, v97, v1
	v_exp_f32_e32 v10, v5
	v_sub_f32_e32 v5, v98, v1
	v_exp_f32_e32 v11, v5
	v_sub_f32_e32 v5, v99, v1
	v_exp_f32_e32 v13, v5
	v_sub_f32_e32 v5, v100, v1
	v_exp_f32_e32 v14, v5
	v_sub_f32_e32 v5, v101, v1
	v_add_f32_e32 v4, v10, v9
	v_exp_f32_e32 v15, v5
	v_sub_f32_e32 v5, v102, v1
	v_add_f32_e32 v4, v11, v4
	v_exp_f32_e32 v96, v5
	v_sub_f32_e32 v5, v103, v1
	v_add_f32_e32 v4, v13, v4
	v_exp_f32_e32 v97, v5
	v_sub_f32_e32 v5, v104, v1
	v_add_f32_e32 v4, v14, v4
	v_exp_f32_e32 v5, v5
	v_sub_f32_e32 v6, v105, v1
	v_add_f32_e32 v4, v15, v4
	v_exp_f32_e32 v6, v6
	v_sub_f32_e32 v7, v106, v1
	v_add_f32_e32 v4, v96, v4
	v_exp_f32_e32 v7, v7
	v_sub_f32_e32 v98, v107, v1
	v_add_f32_e32 v4, v97, v4
	v_exp_f32_e32 v98, v98
	v_sub_f32_e32 v99, v108, v1
	v_add_f32_e32 v4, v5, v4
	v_exp_f32_e32 v99, v99
	v_sub_f32_e32 v100, v109, v1
	v_add_f32_e32 v4, v6, v4
	v_exp_f32_e32 v100, v100
	v_sub_f32_e32 v101, v110, v1
	v_add_f32_e32 v4, v7, v4
	v_exp_f32_e32 v101, v101
	v_sub_f32_e32 v1, v111, v1
	v_add_f32_e32 v4, v98, v4
	v_exp_f32_e32 v1, v1
	v_add_f32_e32 v4, v99, v4
	v_add_f32_e32 v4, v100, v4
	v_add_f32_e32 v4, v101, v4
	v_add_f32_e32 v4, v1, v4
	v_add_f32_e32 v102, v12, v4
	v_cvt_pk_bf16_f32 v4, v5, v6
	v_cvt_pk_bf16_f32 v5, v7, v98
	v_cvt_pk_bf16_f32 v7, v101, v1
	v_sub_f32_e32 v1, v80, v205
	v_cvt_pk_bf16_f32 v12, v9, v10
	v_exp_f32_e32 v1, v1
	v_sub_f32_e32 v10, v81, v205
	v_cvt_pk_bf16_f32 v13, v11, v13
	v_exp_f32_e32 v10, v10
	v_sub_f32_e32 v11, v82, v205
	v_exp_f32_e32 v11, v11
	v_sub_f32_e32 v80, v83, v205
	v_exp_f32_e32 v81, v80
	v_sub_f32_e32 v80, v84, v205
	v_exp_f32_e32 v82, v80
	v_sub_f32_e32 v80, v85, v205
	v_add_f32_e32 v9, v10, v1
	v_exp_f32_e32 v83, v80
	v_sub_f32_e32 v80, v86, v205
	v_add_f32_e32 v9, v11, v9
	v_exp_f32_e32 v84, v80
	v_sub_f32_e32 v80, v87, v205
	v_add_f32_e32 v9, v81, v9
	v_exp_f32_e32 v85, v80
	v_sub_f32_e32 v80, v88, v205
	v_add_f32_e32 v9, v82, v9
	v_exp_f32_e32 v86, v80
	v_sub_f32_e32 v80, v89, v205
	v_add_f32_e32 v9, v83, v9
	v_exp_f32_e32 v87, v80
	v_sub_f32_e32 v80, v90, v205
	v_add_f32_e32 v9, v84, v9
	v_exp_f32_e32 v88, v80
	v_sub_f32_e32 v80, v91, v205
	v_add_f32_e32 v9, v85, v9
	v_exp_f32_e32 v89, v80
	v_sub_f32_e32 v80, v92, v205
	v_add_f32_e32 v9, v86, v9
	v_exp_f32_e32 v90, v80
	v_sub_f32_e32 v80, v93, v205
	v_add_f32_e32 v9, v87, v9
	v_exp_f32_e32 v91, v80
	v_sub_f32_e32 v80, v94, v205
	v_add_f32_e32 v9, v88, v9
	v_exp_f32_e32 v92, v80
	v_sub_f32_e32 v80, v95, v205
	v_add_f32_e32 v9, v89, v9
	v_exp_f32_e32 v93, v80
	v_add_f32_e32 v9, v90, v9
	v_add_f32_e32 v9, v91, v9
	v_add_f32_e32 v9, v92, v9
	v_add_f32_e32 v9, v93, v9
	v_cvt_pk_bf16_f32 v80, v1, v10
	v_lshl_add_u32 v1, v204, 1, v3
	v_cvt_pk_bf16_f32 v14, v14, v15
	v_cvt_pk_bf16_f32 v15, v96, v97
	v_add_f32_e32 v96, v8, v9
	v_cvt_pk_bf16_f32 v82, v82, v83
	v_cvt_pk_bf16_f32 v83, v84, v85
	v_cvt_pk_bf16_f32 v8, v86, v87
	ds_read2st64_b64 v[84:87], v1 offset0:16 offset1:24
	v_lshl_add_u32 v1, v203, 1, v3
	v_cvt_pk_bf16_f32 v9, v88, v89
	v_cvt_pk_bf16_f32 v10, v90, v91
	ds_read2st64_b64 v[88:91], v1 offset0:16 offset1:24
	v_cvt_pk_bf16_f32 v81, v11, v81
	v_cvt_pk_bf16_f32 v11, v92, v93
	s_waitcnt lgkmcnt(0)
	v_mov_b32_e32 v92, v84
	v_mov_b32_e32 v93, v85
	v_mov_b32_e32 v94, v88
	v_mov_b32_e32 v95, v89
	v_mov_b32_e32 v88, v86
	v_mov_b32_e32 v89, v87
	v_lshl_add_u32 v1, v202, 1, v3
	v_mfma_f32_32x32x16_bf16 v[64:79], v[92:95], v[12:15], v[64:79]
	v_cvt_pk_bf16_f32 v6, v99, v100
	s_lshl_b64 s[2:3], s[36:37], 10
	v_readlane_b32 s0, v252, 53
	s_add_u32 s36, s0, s2
	v_readlane_b32 s0, v252, 54
	s_addc_u32 s37, s0, s3
	s_lshl_b32 s2, s38, 1
	v_mfma_f32_32x32x16_bf16 v[48:63], v[88:91], v[12:15], v[48:63]
	ds_read2st64_b64 v[12:15], v1 offset0:16 offset1:24
	v_lshl_add_u32 v1, v201, 1, v3
	s_add_u32 s2, s36, s2
	s_addc_u32 s3, s37, 0
	s_mov_b32 s0, 0x8000
	s_waitcnt lgkmcnt(0)
	v_mov_b32_e32 v84, v12
	v_mov_b32_e32 v85, v13
	v_mfma_f32_32x32x16_bf16 v[32:47], v[92:95], v[80:83], v[32:47]
	v_mfma_f32_32x32x16_bf16 v[16:31], v[88:91], v[80:83], v[16:31]
	ds_read2st64_b64 v[80:83], v1 offset0:16 offset1:24
	ds_bpermute_b32 v1, v0, v102
	ds_bpermute_b32 v0, v0, v96
	s_waitcnt lgkmcnt(0)
	v_mov_b32_e32 v86, v80
	v_mov_b32_e32 v87, v81
	v_mov_b32_e32 v80, v14
	v_mov_b32_e32 v81, v15
	v_mfma_f32_32x32x16_bf16 v[64:79], v[84:87], v[4:7], v[64:79]
	v_add_f32_e32 v1, v102, v1
	v_add_f32_e32 v0, v96, v0
	v_rcp_f32_e32 v0, v0
	v_mfma_f32_32x32x16_bf16 v[32:47], v[84:87], v[8:11], v[32:47]
	v_mfma_f32_32x32x16_bf16 v[16:31], v[80:83], v[8:11], v[16:31]
	v_rcp_f32_e32 v8, v1
	s_nop 5
	v_pk_mul_f32 v[10:11], v[66:67], v[8:9] op_sel_hi:[1,0]
	v_mfma_f32_32x32x16_bf16 v[48:63], v[80:83], v[4:7], v[48:63]
	v_lshlrev_b32_e32 v4, 10, v161
	v_mov_b32_e32 v161, v2
	v_lshl_add_u64 v[6:7], s[2:3], 0, v[160:161]
	v_mov_b32_e32 v5, v2
	v_lshl_add_u64 v[4:5], v[6:7], 0, v[4:5]
	v_pk_mul_f32 v[6:7], v[64:65], v[8:9] op_sel_hi:[1,0]
	s_nop 0
	v_cvt_pk_bf16_f32 v6, v6, v7
	v_cvt_pk_bf16_f32 v7, v10, v11
	global_store_dwordx2 v[4:5], v[6:7], off
	v_pk_mul_f32 v[6:7], v[68:69], v[8:9] op_sel_hi:[1,0]
	v_pk_mul_f32 v[10:11], v[70:71], v[8:9] op_sel_hi:[1,0]
	v_cvt_pk_bf16_f32 v6, v6, v7
	v_cvt_pk_bf16_f32 v7, v10, v11
	global_store_dwordx2 v[4:5], v[6:7], off offset:16
	v_pk_mul_f32 v[6:7], v[72:73], v[8:9] op_sel_hi:[1,0]
	v_pk_mul_f32 v[10:11], v[74:75], v[8:9] op_sel_hi:[1,0]
	v_cvt_pk_bf16_f32 v6, v6, v7
	v_cvt_pk_bf16_f32 v7, v10, v11
	global_store_dwordx2 v[4:5], v[6:7], off offset:32
	v_pk_mul_f32 v[6:7], v[76:77], v[8:9] op_sel_hi:[1,0]
	v_pk_mul_f32 v[10:11], v[78:79], v[8:9] op_sel_hi:[1,0]
	v_cvt_pk_bf16_f32 v6, v6, v7
	v_cvt_pk_bf16_f32 v7, v10, v11
	global_store_dwordx2 v[4:5], v[6:7], off offset:48
	v_pk_mul_f32 v[6:7], v[48:49], v[8:9] op_sel_hi:[1,0]
	v_pk_mul_f32 v[10:11], v[50:51], v[8:9] op_sel_hi:[1,0]
	v_cvt_pk_bf16_f32 v6, v6, v7
	v_cvt_pk_bf16_f32 v7, v10, v11
	global_store_dwordx2 v[4:5], v[6:7], off offset:64
	v_pk_mul_f32 v[6:7], v[52:53], v[8:9] op_sel_hi:[1,0]
	v_pk_mul_f32 v[10:11], v[54:55], v[8:9] op_sel_hi:[1,0]
	v_cvt_pk_bf16_f32 v6, v6, v7
	v_cvt_pk_bf16_f32 v7, v10, v11
	global_store_dwordx2 v[4:5], v[6:7], off offset:80
	v_pk_mul_f32 v[6:7], v[56:57], v[8:9] op_sel_hi:[1,0]
	v_pk_mul_f32 v[10:11], v[58:59], v[8:9] op_sel_hi:[1,0]
	v_cvt_pk_bf16_f32 v6, v6, v7
	v_cvt_pk_bf16_f32 v7, v10, v11
	global_store_dwordx2 v[4:5], v[6:7], off offset:96
	v_pk_mul_f32 v[6:7], v[60:61], v[8:9] op_sel_hi:[1,0]
	v_pk_mul_f32 v[8:9], v[62:63], v[8:9] op_sel_hi:[1,0]
	v_cvt_pk_bf16_f32 v6, v6, v7
	v_cvt_pk_bf16_f32 v7, v8, v9
	global_store_dwordx2 v[4:5], v[6:7], off offset:112
	v_pk_mul_f32 v[6:7], v[32:33], v[0:1] op_sel_hi:[1,0]
	v_pk_mul_f32 v[8:9], v[34:35], v[0:1] op_sel_hi:[1,0]
	v_add_co_u32_e32 v4, vcc, s0, v4
	v_cvt_pk_bf16_f32 v6, v6, v7
	v_cvt_pk_bf16_f32 v7, v8, v9
	v_addc_co_u32_e32 v5, vcc, 0, v5, vcc
	global_store_dwordx2 v[4:5], v[6:7], off
	v_pk_mul_f32 v[6:7], v[36:37], v[0:1] op_sel_hi:[1,0]
	v_pk_mul_f32 v[8:9], v[38:39], v[0:1] op_sel_hi:[1,0]
	v_cvt_pk_bf16_f32 v6, v6, v7
	v_cvt_pk_bf16_f32 v7, v8, v9
	global_store_dwordx2 v[4:5], v[6:7], off offset:16
	v_pk_mul_f32 v[6:7], v[40:41], v[0:1] op_sel_hi:[1,0]
	v_pk_mul_f32 v[8:9], v[42:43], v[0:1] op_sel_hi:[1,0]
	v_cvt_pk_bf16_f32 v6, v6, v7
	v_cvt_pk_bf16_f32 v7, v8, v9
	global_store_dwordx2 v[4:5], v[6:7], off offset:32
	v_pk_mul_f32 v[6:7], v[44:45], v[0:1] op_sel_hi:[1,0]
	v_pk_mul_f32 v[8:9], v[46:47], v[0:1] op_sel_hi:[1,0]
	v_cvt_pk_bf16_f32 v6, v6, v7
	v_cvt_pk_bf16_f32 v7, v8, v9
	global_store_dwordx2 v[4:5], v[6:7], off offset:48
	v_pk_mul_f32 v[6:7], v[16:17], v[0:1] op_sel_hi:[1,0]
	v_pk_mul_f32 v[8:9], v[18:19], v[0:1] op_sel_hi:[1,0]
	v_cvt_pk_bf16_f32 v6, v6, v7
	v_cvt_pk_bf16_f32 v7, v8, v9
	global_store_dwordx2 v[4:5], v[6:7], off offset:64
	v_pk_mul_f32 v[6:7], v[20:21], v[0:1] op_sel_hi:[1,0]
	v_pk_mul_f32 v[8:9], v[22:23], v[0:1] op_sel_hi:[1,0]
	v_cvt_pk_bf16_f32 v6, v6, v7
	v_cvt_pk_bf16_f32 v7, v8, v9
	global_store_dwordx2 v[4:5], v[6:7], off offset:80
	v_pk_mul_f32 v[6:7], v[24:25], v[0:1] op_sel_hi:[1,0]
	v_pk_mul_f32 v[8:9], v[26:27], v[0:1] op_sel_hi:[1,0]
	v_cvt_pk_bf16_f32 v6, v6, v7
	v_cvt_pk_bf16_f32 v7, v8, v9
	global_store_dwordx2 v[4:5], v[6:7], off offset:96
	v_pk_mul_f32 v[6:7], v[28:29], v[0:1] op_sel_hi:[1,0]
	v_pk_mul_f32 v[0:1], v[30:31], v[0:1] op_sel_hi:[1,0]
	v_cvt_pk_bf16_f32 v6, v6, v7
	v_cvt_pk_bf16_f32 v7, v0, v1
	global_store_dwordx2 v[4:5], v[6:7], off offset:112
	s_waitcnt lgkmcnt(0)
	s_waitcnt vmcnt(0)
	s_barrier

.LBB0_294:
	v_sub_f32_e32 v4, v96, v1
	v_exp_f32_e32 v9, v4
	v_sub_f32_e32 v5, v97, v1
	v_exp_f32_e32 v10, v5
	v_sub_f32_e32 v5, v98, v1
	v_exp_f32_e32 v11, v5
	v_sub_f32_e32 v5, v99, v1
	v_exp_f32_e32 v13, v5
	v_sub_f32_e32 v5, v100, v1
	v_exp_f32_e32 v14, v5
	v_sub_f32_e32 v5, v101, v1
	v_add_f32_e32 v4, v10, v9
	v_exp_f32_e32 v15, v5
	v_sub_f32_e32 v5, v102, v1
	v_add_f32_e32 v4, v11, v4
	v_exp_f32_e32 v96, v5
	v_sub_f32_e32 v5, v103, v1
	v_add_f32_e32 v4, v13, v4
	v_exp_f32_e32 v97, v5
	v_sub_f32_e32 v5, v104, v1
	v_add_f32_e32 v4, v14, v4
	v_exp_f32_e32 v5, v5
	v_sub_f32_e32 v6, v105, v1
	v_add_f32_e32 v4, v15, v4
	v_exp_f32_e32 v6, v6
	v_sub_f32_e32 v7, v106, v1
	v_add_f32_e32 v4, v96, v4
	v_exp_f32_e32 v7, v7
	v_sub_f32_e32 v12, v107, v1
	v_add_f32_e32 v4, v97, v4
	v_exp_f32_e32 v12, v12
	v_sub_f32_e32 v98, v108, v1
	v_add_f32_e32 v4, v5, v4
	v_exp_f32_e32 v98, v98
	v_sub_f32_e32 v99, v109, v1
	v_add_f32_e32 v4, v6, v4
	v_exp_f32_e32 v99, v99
	v_sub_f32_e32 v100, v110, v1
	v_add_f32_e32 v4, v7, v4
	v_exp_f32_e32 v100, v100
	v_sub_f32_e32 v101, v111, v1
	v_add_f32_e32 v4, v12, v4
	v_exp_f32_e32 v101, v101
	v_add_f32_e32 v4, v98, v4
	v_add_f32_e32 v4, v99, v4
	v_add_f32_e32 v4, v100, v4
	v_add_f32_e32 v4, v101, v4
	v_add_f32_e32 v3, v3, v4
	v_cvt_pk_bf16_f32 v4, v5, v6
	v_cvt_pk_bf16_f32 v5, v7, v12
	v_cvt_pk_bf16_f32 v12, v9, v10
	v_sub_f32_e32 v9, v80, v159
	v_cvt_pk_bf16_f32 v13, v11, v13
	v_exp_f32_e32 v9, v9
	v_sub_f32_e32 v11, v81, v159
	v_exp_f32_e32 v11, v11
	v_sub_f32_e32 v80, v82, v159
	v_exp_f32_e32 v81, v80
	v_sub_f32_e32 v80, v83, v159
	v_exp_f32_e32 v82, v80
	v_sub_f32_e32 v80, v84, v159
	v_exp_f32_e32 v83, v80
	v_sub_f32_e32 v80, v85, v159
	v_add_f32_e32 v10, v11, v9
	v_exp_f32_e32 v84, v80
	v_sub_f32_e32 v80, v86, v159
	v_add_f32_e32 v10, v81, v10
	v_exp_f32_e32 v85, v80
	v_sub_f32_e32 v80, v87, v159
	v_add_f32_e32 v10, v82, v10
	v_exp_f32_e32 v86, v80
	v_sub_f32_e32 v80, v88, v159
	v_add_f32_e32 v10, v83, v10
	v_exp_f32_e32 v87, v80
	v_sub_f32_e32 v80, v89, v159
	v_add_f32_e32 v10, v84, v10
	v_exp_f32_e32 v88, v80
	v_sub_f32_e32 v80, v90, v159
	v_add_f32_e32 v10, v85, v10
	v_exp_f32_e32 v89, v80
	v_sub_f32_e32 v80, v91, v159
	v_add_f32_e32 v10, v86, v10
	v_exp_f32_e32 v90, v80
	v_sub_f32_e32 v80, v92, v159
	v_add_f32_e32 v10, v87, v10
	v_exp_f32_e32 v91, v80
	v_sub_f32_e32 v80, v93, v159
	v_add_f32_e32 v10, v88, v10
	v_exp_f32_e32 v92, v80
	v_sub_f32_e32 v80, v94, v159
	v_add_f32_e32 v10, v89, v10
	v_exp_f32_e32 v93, v80
	v_sub_f32_e32 v80, v95, v159
	v_add_f32_e32 v10, v90, v10
	v_exp_f32_e32 v94, v80
	v_add_f32_e32 v10, v91, v10
	v_add_f32_e32 v10, v92, v10
	v_add_f32_e32 v10, v93, v10
	v_add_f32_e32 v10, v94, v10
	v_add_f32_e32 v162, v8, v10
	v_cvt_pk_bf16_f32 v81, v81, v82
	v_cvt_pk_bf16_f32 v82, v83, v84
	v_cvt_pk_bf16_f32 v8, v87, v88
	v_lshl_add_u32 v84, v158, 1, v204
	v_lshl_add_u32 v88, v157, 1, v204
	v_cvt_pk_bf16_f32 v80, v9, v11
	v_cvt_pk_bf16_f32 v83, v85, v86
	v_cvt_pk_bf16_f32 v9, v89, v90
	v_cvt_pk_bf16_f32 v10, v91, v92
	ds_read_b64 v[222:223], v84 offset:8192
	ds_read_b64 v[226:227], v84 offset:12288
	ds_read_b64 v[224:225], v88 offset:8192
	ds_read_b64 v[228:229], v88 offset:12288
	v_cvt_pk_bf16_f32 v11, v93, v94
	v_cvt_pk_bf16_f32 v14, v14, v15
	v_cvt_pk_bf16_f32 v15, v96, v97
	s_waitcnt lgkmcnt(0)
	v_mfma_f32_32x32x16_bf16 v[64:79], v[222:225], v[12:15], v[64:79]
	v_cvt_pk_bf16_f32 v6, v98, v99
	v_cvt_pk_bf16_f32 v7, v100, v101
	s_add_i32 s40, s40, 1
	s_add_i32 s2, s41, 1
	s_cmp_lg_u32 s41, 2
	s_cselect_b32 s41, s2, 0
	s_mov_b64 s[2:3], 0x2000
	v_mfma_f32_32x32x16_bf16 v[32:47], v[222:225], v[80:83], v[32:47]
	v_lshl_add_u64 v[150:151], v[150:151], 0, s[22:23]
	v_lshl_add_u64 v[152:153], v[152:153], 0, s[2:3]
	s_cmp_lg_u32 s40, 39
	v_mfma_f32_32x32x16_bf16 v[48:63], v[226:229], v[12:15], v[48:63]
	v_lshl_add_u32 v12, v156, 1, v204
	ds_read2st64_b64 v[12:15], v12 offset0:16 offset1:24
	s_waitcnt lgkmcnt(0)
	v_mov_b32_e32 v84, v12
	v_mfma_f32_32x32x16_bf16 v[16:31], v[226:229], v[80:83], v[16:31]
	v_lshl_add_u32 v80, v155, 1, v204
	ds_read2st64_b64 v[80:83], v80 offset0:16 offset1:24
	v_mov_b32_e32 v85, v13
	s_waitcnt lgkmcnt(0)
	v_mov_b32_e32 v86, v80
	v_mov_b32_e32 v87, v81
	v_mov_b32_e32 v80, v14
	v_mov_b32_e32 v81, v15
	v_mfma_f32_32x32x16_bf16 v[64:79], v[84:87], v[4:7], v[64:79]
	v_mfma_f32_32x32x16_bf16 v[32:47], v[84:87], v[8:11], v[32:47]
	v_mfma_f32_32x32x16_bf16 v[48:63], v[80:83], v[4:7], v[48:63]
	v_mfma_f32_32x32x16_bf16 v[16:31], v[80:83], v[8:11], v[16:31]
	s_cbranch_scc0 .LBB0_305

.LBB0_313:
	v_sub_f32_e32 v4, v96, v1
	v_exp_f32_e32 v9, v4
	v_sub_f32_e32 v5, v97, v1
	v_exp_f32_e32 v10, v5
	v_sub_f32_e32 v5, v98, v1
	v_exp_f32_e32 v11, v5
	v_sub_f32_e32 v5, v99, v1
	v_exp_f32_e32 v13, v5
	v_sub_f32_e32 v5, v100, v1
	v_exp_f32_e32 v14, v5
	v_sub_f32_e32 v5, v101, v1
	v_add_f32_e32 v4, v10, v9
	v_exp_f32_e32 v15, v5
	v_sub_f32_e32 v5, v102, v1
	v_add_f32_e32 v4, v11, v4
	v_exp_f32_e32 v96, v5
	v_sub_f32_e32 v5, v103, v1
	v_add_f32_e32 v4, v13, v4
	v_exp_f32_e32 v97, v5
	v_sub_f32_e32 v5, v104, v1
	v_add_f32_e32 v4, v14, v4
	v_exp_f32_e32 v5, v5
	v_sub_f32_e32 v6, v105, v1
	v_add_f32_e32 v4, v15, v4
	v_exp_f32_e32 v6, v6
	v_sub_f32_e32 v7, v106, v1
	v_add_f32_e32 v4, v96, v4
	v_exp_f32_e32 v7, v7
	v_sub_f32_e32 v98, v107, v1
	v_add_f32_e32 v4, v97, v4
	v_exp_f32_e32 v98, v98
	v_sub_f32_e32 v99, v108, v1
	v_add_f32_e32 v4, v5, v4
	v_exp_f32_e32 v99, v99
	v_sub_f32_e32 v100, v109, v1
	v_add_f32_e32 v4, v6, v4
	v_exp_f32_e32 v100, v100
	v_sub_f32_e32 v101, v110, v1
	v_add_f32_e32 v4, v7, v4
	v_exp_f32_e32 v101, v101
	v_sub_f32_e32 v1, v111, v1
	v_add_f32_e32 v4, v98, v4
	v_exp_f32_e32 v1, v1
	v_add_f32_e32 v4, v99, v4
	v_add_f32_e32 v4, v100, v4
	v_add_f32_e32 v4, v101, v4
	v_add_f32_e32 v4, v1, v4
	v_add_f32_e32 v102, v12, v4
	v_cvt_pk_bf16_f32 v4, v5, v6
	v_cvt_pk_bf16_f32 v5, v7, v98
	v_cvt_pk_bf16_f32 v7, v101, v1
	v_sub_f32_e32 v1, v80, v159
	v_cvt_pk_bf16_f32 v12, v9, v10
	v_exp_f32_e32 v1, v1
	v_sub_f32_e32 v10, v81, v159
	v_cvt_pk_bf16_f32 v13, v11, v13
	v_exp_f32_e32 v10, v10
	v_sub_f32_e32 v11, v82, v159
	v_exp_f32_e32 v11, v11
	v_sub_f32_e32 v80, v83, v159
	v_exp_f32_e32 v81, v80
	v_sub_f32_e32 v80, v84, v159
	v_exp_f32_e32 v82, v80
	v_sub_f32_e32 v80, v85, v159
	v_add_f32_e32 v9, v10, v1
	v_exp_f32_e32 v83, v80
	v_sub_f32_e32 v80, v86, v159
	v_add_f32_e32 v9, v11, v9
	v_exp_f32_e32 v84, v80
	v_sub_f32_e32 v80, v87, v159
	v_add_f32_e32 v9, v81, v9
	v_exp_f32_e32 v85, v80
	v_sub_f32_e32 v80, v88, v159
	v_add_f32_e32 v9, v82, v9
	v_exp_f32_e32 v86, v80
	v_sub_f32_e32 v80, v89, v159
	v_add_f32_e32 v9, v83, v9
	v_exp_f32_e32 v87, v80
	v_sub_f32_e32 v80, v90, v159
	v_add_f32_e32 v9, v84, v9
	v_exp_f32_e32 v88, v80
	v_sub_f32_e32 v80, v91, v159
	v_add_f32_e32 v9, v85, v9
	v_exp_f32_e32 v89, v80
	v_sub_f32_e32 v80, v92, v159
	v_add_f32_e32 v9, v86, v9
	v_exp_f32_e32 v90, v80
	v_sub_f32_e32 v80, v93, v159
	v_add_f32_e32 v9, v87, v9
	v_exp_f32_e32 v91, v80
	v_sub_f32_e32 v80, v94, v159
	v_add_f32_e32 v9, v88, v9
	v_exp_f32_e32 v92, v80
	v_sub_f32_e32 v80, v95, v159
	v_add_f32_e32 v9, v89, v9
	v_exp_f32_e32 v93, v80
	v_add_f32_e32 v9, v90, v9
	v_add_f32_e32 v9, v91, v9
	v_add_f32_e32 v9, v92, v9
	v_add_f32_e32 v9, v93, v9
	v_cvt_pk_bf16_f32 v80, v1, v10
	v_lshl_add_u32 v1, v158, 1, v3
	v_cvt_pk_bf16_f32 v14, v14, v15
	v_cvt_pk_bf16_f32 v15, v96, v97
	v_add_f32_e32 v96, v8, v9
	v_cvt_pk_bf16_f32 v82, v82, v83
	v_cvt_pk_bf16_f32 v83, v84, v85
	v_cvt_pk_bf16_f32 v8, v86, v87
	ds_read2st64_b64 v[84:87], v1 offset0:16 offset1:24
	v_lshl_add_u32 v1, v157, 1, v3
	v_cvt_pk_bf16_f32 v9, v88, v89
	v_cvt_pk_bf16_f32 v10, v90, v91
	ds_read2st64_b64 v[88:91], v1 offset0:16 offset1:24
	v_cvt_pk_bf16_f32 v81, v11, v81
	v_cvt_pk_bf16_f32 v11, v92, v93
	s_waitcnt lgkmcnt(0)
	v_mov_b32_e32 v92, v84
	v_mov_b32_e32 v93, v85
	v_mov_b32_e32 v94, v88
	v_mov_b32_e32 v95, v89
	v_mov_b32_e32 v88, v86
	v_mov_b32_e32 v89, v87
	v_lshl_add_u32 v1, v156, 1, v3
	v_mfma_f32_32x32x16_bf16 v[64:79], v[92:95], v[12:15], v[64:79]
	v_cvt_pk_bf16_f32 v6, v99, v100
	s_lshl_b64 s[2:3], s[38:39], 1
	v_readlane_b32 s18, v252, 51
	v_readlane_b32 s19, v252, 52
	s_add_u32 s38, s18, s2
	s_addc_u32 s39, s19, s3
	s_add_u32 s2, s38, s36
	v_mfma_f32_32x32x16_bf16 v[48:63], v[88:91], v[12:15], v[48:63]
	ds_read2st64_b64 v[12:15], v1 offset0:16 offset1:24
	v_lshl_add_u32 v1, v155, 1, v3
	s_addc_u32 s3, s39, s37
	s_waitcnt lgkmcnt(0)
	v_mov_b32_e32 v84, v12
	v_mov_b32_e32 v85, v13
	v_mfma_f32_32x32x16_bf16 v[32:47], v[92:95], v[80:83], v[32:47]
	v_mfma_f32_32x32x16_bf16 v[16:31], v[88:91], v[80:83], v[16:31]
	ds_read2st64_b64 v[80:83], v1 offset0:16 offset1:24
	ds_bpermute_b32 v1, v0, v102
	ds_bpermute_b32 v0, v0, v96
	s_waitcnt lgkmcnt(0)
	v_mov_b32_e32 v86, v80
	v_mov_b32_e32 v87, v81
	v_mov_b32_e32 v80, v14
	v_mov_b32_e32 v81, v15
	v_mfma_f32_32x32x16_bf16 v[64:79], v[84:87], v[4:7], v[64:79]
	v_add_f32_e32 v1, v102, v1
	v_add_f32_e32 v0, v96, v0
	v_rcp_f32_e32 v0, v0
	v_mfma_f32_32x32x16_bf16 v[48:63], v[80:83], v[4:7], v[48:63]
	v_rcp_f32_e32 v6, v1
	v_lshlrev_b32_e32 v4, 1, v154
	v_mov_b32_e32 v5, v2
	v_lshl_add_u64 v[4:5], s[2:3], 0, v[4:5]
	s_nop 3
	v_pk_mul_f32 v[12:13], v[66:67], v[6:7] op_sel_hi:[1,0]
	v_mfma_f32_32x32x16_bf16 v[32:47], v[84:87], v[8:11], v[32:47]
	v_mfma_f32_32x32x16_bf16 v[16:31], v[80:83], v[8:11], v[16:31]
	v_mul_f32_e64 v10, v64, v6
	v_mul_f32_e64 v11, v65, v6
	v_lshl_add_u64 v[8:9], v[4:5], 0, v[146:147]
	v_cvt_pk_bf16_f32 v10, v10, v11
	v_cvt_pk_bf16_f32 v11, v12, v13
	global_store_dwordx2 v[8:9], v[10:11], off
	v_pk_mul_f32 v[10:11], v[68:69], v[6:7] op_sel_hi:[1,0]
	v_pk_mul_f32 v[12:13], v[70:71], v[6:7] op_sel_hi:[1,0]
	v_cvt_pk_bf16_f32 v10, v10, v11
	v_cvt_pk_bf16_f32 v11, v12, v13
	global_store_dwordx2 v[8:9], v[10:11], off offset:16
	v_pk_mul_f32 v[10:11], v[72:73], v[6:7] op_sel_hi:[1,0]
	v_pk_mul_f32 v[12:13], v[74:75], v[6:7] op_sel_hi:[1,0]
	v_cvt_pk_bf16_f32 v10, v10, v11
	v_cvt_pk_bf16_f32 v11, v12, v13
	global_store_dwordx2 v[8:9], v[10:11], off offset:32
	v_pk_mul_f32 v[10:11], v[76:77], v[6:7] op_sel_hi:[1,0]
	v_pk_mul_f32 v[12:13], v[78:79], v[6:7] op_sel_hi:[1,0]
	v_cvt_pk_bf16_f32 v10, v10, v11
	v_cvt_pk_bf16_f32 v11, v12, v13
	global_store_dwordx2 v[8:9], v[10:11], off offset:48
	v_pk_mul_f32 v[10:11], v[48:49], v[6:7] op_sel_hi:[1,0]
	v_pk_mul_f32 v[12:13], v[50:51], v[6:7] op_sel_hi:[1,0]
	v_cvt_pk_bf16_f32 v10, v10, v11
	v_cvt_pk_bf16_f32 v11, v12, v13
	global_store_dwordx2 v[8:9], v[10:11], off offset:64
	v_pk_mul_f32 v[10:11], v[52:53], v[6:7] op_sel_hi:[1,0]
	v_pk_mul_f32 v[12:13], v[54:55], v[6:7] op_sel_hi:[1,0]
	v_cvt_pk_bf16_f32 v10, v10, v11
	v_cvt_pk_bf16_f32 v11, v12, v13
	global_store_dwordx2 v[8:9], v[10:11], off offset:80
	v_pk_mul_f32 v[10:11], v[56:57], v[6:7] op_sel_hi:[1,0]
	v_pk_mul_f32 v[12:13], v[58:59], v[6:7] op_sel_hi:[1,0]
	v_cvt_pk_bf16_f32 v10, v10, v11
	v_cvt_pk_bf16_f32 v11, v12, v13
	global_store_dwordx2 v[8:9], v[10:11], off offset:96
	v_pk_mul_f32 v[10:11], v[60:61], v[6:7] op_sel_hi:[1,0]
	v_pk_mul_f32 v[6:7], v[62:63], v[6:7] op_sel_hi:[1,0]
	v_cvt_pk_bf16_f32 v10, v10, v11
	v_cvt_pk_bf16_f32 v11, v6, v7
	global_store_dwordx2 v[8:9], v[10:11], off offset:112
	v_pk_mul_f32 v[6:7], v[32:33], v[0:1] op_sel_hi:[1,0]
	v_pk_mul_f32 v[8:9], v[34:35], v[0:1] op_sel_hi:[1,0]
	v_lshl_add_u64 v[4:5], v[4:5], 0, v[144:145]
	v_cvt_pk_bf16_f32 v6, v6, v7
	v_cvt_pk_bf16_f32 v7, v8, v9
	global_store_dwordx2 v[4:5], v[6:7], off
	v_pk_mul_f32 v[6:7], v[36:37], v[0:1] op_sel_hi:[1,0]
	v_pk_mul_f32 v[8:9], v[38:39], v[0:1] op_sel_hi:[1,0]
	v_cvt_pk_bf16_f32 v6, v6, v7
	v_cvt_pk_bf16_f32 v7, v8, v9
	global_store_dwordx2 v[4:5], v[6:7], off offset:16
	v_pk_mul_f32 v[6:7], v[40:41], v[0:1] op_sel_hi:[1,0]
	v_pk_mul_f32 v[8:9], v[42:43], v[0:1] op_sel_hi:[1,0]
	v_cvt_pk_bf16_f32 v6, v6, v7
	v_cvt_pk_bf16_f32 v7, v8, v9
	global_store_dwordx2 v[4:5], v[6:7], off offset:32
	v_pk_mul_f32 v[6:7], v[44:45], v[0:1] op_sel_hi:[1,0]
	v_pk_mul_f32 v[8:9], v[46:47], v[0:1] op_sel_hi:[1,0]
	v_cvt_pk_bf16_f32 v6, v6, v7
	v_cvt_pk_bf16_f32 v7, v8, v9
	global_store_dwordx2 v[4:5], v[6:7], off offset:48
	v_pk_mul_f32 v[6:7], v[16:17], v[0:1] op_sel_hi:[1,0]
	v_pk_mul_f32 v[8:9], v[18:19], v[0:1] op_sel_hi:[1,0]
	v_cvt_pk_bf16_f32 v6, v6, v7
	v_cvt_pk_bf16_f32 v7, v8, v9
	global_store_dwordx2 v[4:5], v[6:7], off offset:64
	v_pk_mul_f32 v[6:7], v[20:21], v[0:1] op_sel_hi:[1,0]
	v_pk_mul_f32 v[8:9], v[22:23], v[0:1] op_sel_hi:[1,0]
	v_cvt_pk_bf16_f32 v6, v6, v7
	v_cvt_pk_bf16_f32 v7, v8, v9
	global_store_dwordx2 v[4:5], v[6:7], off offset:80
	v_pk_mul_f32 v[6:7], v[24:25], v[0:1] op_sel_hi:[1,0]
	v_pk_mul_f32 v[8:9], v[26:27], v[0:1] op_sel_hi:[1,0]
	v_cvt_pk_bf16_f32 v6, v6, v7
	v_cvt_pk_bf16_f32 v7, v8, v9
	global_store_dwordx2 v[4:5], v[6:7], off offset:96
	v_pk_mul_f32 v[6:7], v[28:29], v[0:1] op_sel_hi:[1,0]
	v_pk_mul_f32 v[0:1], v[30:31], v[0:1] op_sel_hi:[1,0]
	v_cvt_pk_bf16_f32 v6, v6, v7
	v_cvt_pk_bf16_f32 v7, v0, v1
	global_store_dwordx2 v[4:5], v[6:7], off offset:112
	s_waitcnt lgkmcnt(0)
	s_waitcnt vmcnt(0)
	s_barrier
